# NA unit: Q-fragment loads + first tile loads issued together with counted waits (was 8 serialized load/wait/ds_write)
# speedup vs baseline: 1.0026x; 1.0013x over previous
; __device__ __forceinline__ int v_st(int k, int c) { const int kk = (k & ~0xC) | ((k & 4) << 1) | ((k & 8) >> 1); return ((kk >> 3) * 4 + (c >> 5)) * 512 + ((kk & 7) * 32 + (c & 31)) * 2; }
; __device__ __forceinline__ int v_rd_base(int lane) { return ((lane & 3) << 3) | (((lane >> 2) & 3) << 6) | (((lane >> 4) & 1) << 5) | (((lane >> 5) & 1) << 8); }
; #define NA_SLOAD(j) do { const long _k0 = NA_TROW(j); vs0 = *reinterpret_cast<const bf16x8*>(&Vh[(_k0 + sr) * LDP + sc]); vs1 = *reinterpret_cast<const bf16x8*>(&Vh[(_k0 + 32 + sr) * LDP + sc]); \
;     ks0 = *reinterpret_cast<const bf16x8*>(&Kh[(_k0 + sr) * LDP + sc]); ks1 = *reinterpret_cast<const bf16x8*>(&Kh[(_k0 + 32 + sr) * LDP + sc]); } while (0)
; template <int LDP, int LDO> ...
;     ...
;   bf16x8* qs = (bf16x8*)(lds + QS_OFF + wid * 8192) + lane;
;   { const bf16* Qw = P + (qrow0 + wid * QBLK + r32) * LDP + qcol + hi * 8;
; #pragma unroll
;     for (int d0 = 0; d0 < 8; ++d0) qs[d0 * 64] = *reinterpret_cast<const bf16x8*>(Qw + d0 * 16); }
;   const int sr = tid >> 4, sc = (tid & 15) * 8, vst0 = v_st(sr, sc), vst1 = v_st(32 + sr, sc);
;   const int vb0 = (int)(uintptr_t)V_lds + v_rd_base(lane);
;   const int qrow = qg0 + (wid >> 1), qc = (wid & 1) * 32 + r32;
;   const float* bt_l = blds + 64 + 15 - qc + 4 * hi; const float* pen_l = pens + 48 - min(max(qc - 8, 0), 48) + 4 * hi;
;   const bf16* Kh = P + kcol; const bf16* Vh = P + vcol;
;   bf16x8 vs0, vs1, ks0, ks1;
;     ...
;   f32x16 p0, p1; float mn, al; bf16x8 pa0, pa1, pa2, pa3; const int NT = 4 + nband; const int rs_ = min(max(qrow - 4, 0), 56);
;   NA_SLOAD(0);
.LBB0_618:
	s_cmp_lt_i32 s18, 16
	s_cbranch_scc1 .LBB0_617
	s_bfe_u32 s0, s9, 0x170008
	s_lshl_b32 s6, s8, 1
	s_mul_hi_u32 s1, s0, 0x320000
	s_mul_i32 s0, s0, 0x320000
	s_and_b32 s6, s6, 0x700
	s_or_b32 s0, s0, s6
	v_lshl_add_u64 v[148:149], v[142:143], 0, s[0:1]
	s_lshl_b32 s0, s18, 7
	s_and_b32 s19, s0, 0x380
	s_lshl_b32 s0, s18, 5
	s_and_b32 s0, s0, 0x7fffff00
	s_add_i32 s30, s0, 0x3e00
	v_lshl_add_u64 v[146:147], s[30:31], 0, v[132:133]
	v_or_b32_e32 v2, v146, v130
	v_mov_b64_e32 v[4:5], s[44:45]
	s_movk_i32 s3, 0x3200
	v_mad_u64_u32 v[4:5], s[0:1], v2, s3, v[4:5]
	v_mad_i32_i24 v5, v147, s3, v5
	s_lshl_b32 s0, s19, 1
	s_mov_b32 s1, s31
	v_lshl_add_u64 v[4:5], v[4:5], 0, s[0:1]
	v_mov_b32_e32 v145, v3
	v_lshl_add_u64 v[8:9], v[4:5], 0, v[144:145]
	s_barrier
	global_load_dwordx4 v[20:23], v[8:9], off
	global_load_dwordx4 v[24:27], v[8:9], off offset:32
	global_load_dwordx4 v[28:31], v[8:9], off offset:64
	global_load_dwordx4 v[36:39], v[8:9], off offset:96
	global_load_dwordx4 v[40:43], v[8:9], off offset:128
	global_load_dwordx4 v[44:47], v[8:9], off offset:160
	global_load_dwordx4 v[52:55], v[8:9], off offset:192
	global_load_dwordx4 v[56:59], v[8:9], off offset:224
	s_add_u32 s0, s44, s0
	s_addc_u32 s1, s45, 0
	s_add_u32 s6, s0, 0x1000
	s_addc_u32 s7, s1, 0
	v_mov_b32_e32 v16, v3
	v_mov_b32_e32 v17, v3
	v_mov_b32_e32 v2, v3
	v_mov_b32_e32 v10, v3
	v_mov_b32_e32 v11, v3
	v_mov_b32_e32 v12, v3
	v_mov_b32_e32 v13, v3
	v_mov_b32_e32 v14, v3
	v_mov_b32_e32 v15, v3
	s_mov_b32 s20, 0
	v_mov_b32_e32 v181, 0
	v_mov_b32_e32 v145, 0xf149f2ca
	v_lshl_add_u64 v[4:5], s[30:31], 0, v[134:135]
	v_mad_u64_u32 v[6:7], s[12:13], v4, s34, 0
	v_mad_i32_i24 v5, v5, s34, v7
	v_or_b32_e32 v4, v6, v136
	v_lshlrev_b64 v[4:5], 1, v[4:5]
	v_lshl_add_u64 v[6:7], s[6:7], 0, v[4:5]
	v_lshl_add_u64 v[4:5], s[0:1], 0, v[4:5]
	global_load_dwordx4 v[114:117], v[6:7], off
	global_load_dwordx4 v[122:125], v[4:5], off offset:2048
	v_lshl_add_u64 v[6:7], v[138:139], 0, s[30:31]
	v_mad_u64_u32 v[8:9], s[12:13], v6, s34, 0
	v_mad_i32_i24 v7, v7, s34, v9
	v_or_b32_e32 v6, v8, v136
	v_lshlrev_b64 v[6:7], 1, v[6:7]
	v_lshl_add_u64 v[8:9], s[6:7], 0, v[6:7]
	v_lshl_add_u64 v[4:5], s[0:1], 0, v[6:7]
	global_load_dwordx4 v[118:121], v[8:9], off
	global_load_dwordx4 v[126:129], v[4:5], off offset:2048
	s_waitcnt vmcnt(11)
	ds_write_b128 v180, v[20:23]
	s_waitcnt vmcnt(10)
	ds_write_b128 v180, v[24:27] offset:1024
	s_waitcnt vmcnt(9)
	ds_write_b128 v180, v[28:31] offset:2048
	s_waitcnt vmcnt(8)
	ds_write_b128 v180, v[36:39] offset:3072
	s_waitcnt vmcnt(7)
	ds_write_b128 v180, v[40:43] offset:4096
	s_waitcnt vmcnt(6)
	ds_write_b128 v180, v[44:47] offset:5120
	s_waitcnt vmcnt(5)
	ds_write_b128 v180, v[52:55] offset:6144
	s_waitcnt vmcnt(4)
	ds_write_b128 v180, v[56:59] offset:7168
	v_mov_b32_e32 v4, v3
	v_mov_b32_e32 v5, v3
	v_mov_b32_e32 v6, v3
	v_mov_b32_e32 v7, v3
	v_mov_b32_e32 v8, v3
	v_mov_b32_e32 v9, v3
	v_mov_b64_e32 v[64:65], v[16:17]
	v_mov_b64_e32 v[48:49], v[16:17]
	v_mov_b64_e32 v[32:33], v[16:17]
	v_mov_b64_e32 v[80:81], v[16:17]
	s_mov_b64 s[0:1], 0
	v_mov_b64_e32 v[62:63], v[14:15]
	v_mov_b64_e32 v[60:61], v[12:13]
	v_mov_b64_e32 v[58:59], v[10:11]
	v_mov_b64_e32 v[56:57], v[8:9]
	v_mov_b64_e32 v[54:55], v[6:7]
	v_mov_b64_e32 v[52:53], v[4:5]
	v_mov_b64_e32 v[50:51], v[2:3]
	v_mov_b64_e32 v[46:47], v[14:15]
	v_mov_b64_e32 v[44:45], v[12:13]
	v_mov_b64_e32 v[42:43], v[10:11]
	v_mov_b64_e32 v[40:41], v[8:9]
	v_mov_b64_e32 v[38:39], v[6:7]
	v_mov_b64_e32 v[36:37], v[4:5]
	v_mov_b64_e32 v[34:35], v[2:3]
	v_mov_b64_e32 v[30:31], v[14:15]
	v_mov_b64_e32 v[28:29], v[12:13]
	v_mov_b64_e32 v[26:27], v[10:11]
	v_mov_b64_e32 v[24:25], v[8:9]
	v_mov_b64_e32 v[22:23], v[6:7]
	v_mov_b64_e32 v[20:21], v[4:5]
	v_mov_b64_e32 v[18:19], v[2:3]
	v_mov_b64_e32 v[78:79], v[14:15]
	v_mov_b64_e32 v[76:77], v[12:13]
	v_mov_b64_e32 v[74:75], v[10:11]
	v_mov_b64_e32 v[72:73], v[8:9]
	v_mov_b64_e32 v[70:71], v[6:7]
	v_mov_b64_e32 v[68:69], v[4:5]
	v_mov_b64_e32 v[66:67], v[2:3]
